# scan phase rewritten by hand: 192 WGs, 32-chunk segments per thread, all loads in flight, LDS carry exchange
# speedup vs baseline: 1.0140x; 1.0112x over previous
; __device__ __forceinline__ unsigned cvt_pk_bf16(float lo, float hi) { unsigned r; asm volatile("v_cvt_pk_bf16_f32 %0, %1, %2" : "=v"(r) : "v"(lo), "v"(hi)); return r; }
; #define GAS __attribute__((address_space(1)))
; __device__ __forceinline__ float lg2_gamma(int h) { return log2f(1.0f - __builtin_amdgcn_exp2f(-5.0f - (float)h)); }
; __device__ __forceinline__ void scan_phase(const GAS float* kvT, GAS bf16_t* st, int tid, int G, int bid) {
;     for (int idx = bid * 512 + tid; idx < 24576; idx += G * 512) {
;         const int h = idx >> 12; const float dec = __builtin_amdgcn_exp2f(lg2_gamma(h) * 128.0f);
;         float S = 0.f;
;         for (int n0 = 0; n0 < 128; n0 += 64) {
;             float kv[64];
; #pragma unroll
;             for (int i = 0; i < 64; ++i) kv[i] = kvT[(size_t)(n0 + i) * 24576 + idx];
; #pragma unroll
;             for (int i = 0; i < 64; ++i) { st[(size_t)(n0 + i) * 24576 + idx] = (bf16_t)(cvt_pk_bf16(S, 0.f) & 0xffffu); S = S * dec + kv[i]; }
.LBB0_365:
	s_and_b64 vcc, exec, s[0:1]
	s_cbranch_vccz .LBB0_391
	s_cmp_gt_i32 s14, 0
	s_mov_b64 s[0:1], -1
	s_cbranch_scc0 .LBB0_451
	s_add_u32 s8, s22, 0x10200000
	s_addc_u32 s9, s23, 0
	v_writelane_b32 v255, s52, 0
	s_cmp_gt_i32 s14, 1
	s_nop 0
	v_writelane_b32 v255, s53, 1
	s_cbranch_scc0 .LBB0_374
	v_readlane_b32 s0, v254, 47
	s_mov_b64 s[2:3], exec
	s_cmp_gt_u32 s0, 0xbf
	s_cbranch_scc1 .LBB0_373
	v_lshrrev_b32_e32 v1, 7, v0
	v_and_b32_e32 v2, 0x7f, v0
	s_lshr_b32 s10, s0, 5
	v_lshl_add_u32 v3, s0, 7, v2
	v_cvt_f32_i32_e32 v4, s10
	v_mul_u32_u24_e32 v6, 0x300000, v1
	v_sub_f32_e32 v4, 0xc0a00000, v4
	v_exp_f32_e32 v4, v4
	v_lshl_add_u32 v6, v3, 2, v6
	global_load_dword v10, v6, s[8:9]
	v_add_u32_e32 v6, 0x18000, v6
	global_load_dword v11, v6, s[8:9]
	v_add_u32_e32 v6, 0x18000, v6
	global_load_dword v12, v6, s[8:9]
	v_add_u32_e32 v6, 0x18000, v6
	global_load_dword v13, v6, s[8:9]
	v_add_u32_e32 v6, 0x18000, v6
	global_load_dword v14, v6, s[8:9]
	v_add_u32_e32 v6, 0x18000, v6
	global_load_dword v15, v6, s[8:9]
	v_add_u32_e32 v6, 0x18000, v6
	global_load_dword v16, v6, s[8:9]
	v_add_u32_e32 v6, 0x18000, v6
	global_load_dword v17, v6, s[8:9]
	v_add_u32_e32 v6, 0x18000, v6
	global_load_dword v18, v6, s[8:9]
	v_add_u32_e32 v6, 0x18000, v6
	global_load_dword v19, v6, s[8:9]
	v_add_u32_e32 v6, 0x18000, v6
	global_load_dword v20, v6, s[8:9]
	v_add_u32_e32 v6, 0x18000, v6
	global_load_dword v21, v6, s[8:9]
	v_add_u32_e32 v6, 0x18000, v6
	global_load_dword v22, v6, s[8:9]
	v_add_u32_e32 v6, 0x18000, v6
	global_load_dword v23, v6, s[8:9]
	v_add_u32_e32 v6, 0x18000, v6
	global_load_dword v24, v6, s[8:9]
	v_add_u32_e32 v6, 0x18000, v6
	global_load_dword v25, v6, s[8:9]
	v_add_u32_e32 v6, 0x18000, v6
	global_load_dword v26, v6, s[8:9]
	v_add_u32_e32 v6, 0x18000, v6
	global_load_dword v27, v6, s[8:9]
	v_add_u32_e32 v6, 0x18000, v6
	global_load_dword v28, v6, s[8:9]
	v_add_u32_e32 v6, 0x18000, v6
	global_load_dword v29, v6, s[8:9]
	v_add_u32_e32 v6, 0x18000, v6
	global_load_dword v30, v6, s[8:9]
	v_add_u32_e32 v6, 0x18000, v6
	global_load_dword v31, v6, s[8:9]
	v_add_u32_e32 v6, 0x18000, v6
	global_load_dword v32, v6, s[8:9]
	v_add_u32_e32 v6, 0x18000, v6
	global_load_dword v33, v6, s[8:9]
	v_add_u32_e32 v6, 0x18000, v6
	global_load_dword v34, v6, s[8:9]
	v_add_u32_e32 v6, 0x18000, v6
	global_load_dword v35, v6, s[8:9]
	v_add_u32_e32 v6, 0x18000, v6
	global_load_dword v36, v6, s[8:9]
	v_add_u32_e32 v6, 0x18000, v6
	global_load_dword v37, v6, s[8:9]
	v_add_u32_e32 v6, 0x18000, v6
	global_load_dword v38, v6, s[8:9]
	v_add_u32_e32 v6, 0x18000, v6
	global_load_dword v39, v6, s[8:9]
	v_add_u32_e32 v6, 0x18000, v6
	global_load_dword v40, v6, s[8:9]
	v_add_u32_e32 v6, 0x18000, v6
	global_load_dword v41, v6, s[8:9]
	v_sub_f32_e32 v4, 1.0, v4
	v_log_f32_e32 v4, v4
	v_mov_b32_e32 v42, 0
	v_mul_f32_e32 v4, 0x43000000, v4
	v_exp_f32_e32 v4, v4
	v_lshlrev_b32_e32 v7, 2, v0
	v_mul_f32_e32 v5, v4, v4
	v_lshlrev_b32_e32 v8, 2, v2
	v_mul_f32_e32 v5, v5, v5
	v_mul_f32_e32 v5, v5, v5
	v_mul_f32_e32 v5, v5, v5
	v_mul_f32_e32 v5, v5, v5
	s_waitcnt vmcnt(31)
	v_fma_f32 v43, v4, v42, v10
	s_waitcnt vmcnt(30)
	v_fma_f32 v44, v4, v43, v11
	s_waitcnt vmcnt(29)
	v_fma_f32 v45, v4, v44, v12
	s_waitcnt vmcnt(28)
	v_fma_f32 v46, v4, v45, v13
	s_waitcnt vmcnt(27)
	v_fma_f32 v47, v4, v46, v14
	s_waitcnt vmcnt(26)
	v_fma_f32 v48, v4, v47, v15
	s_waitcnt vmcnt(25)
	v_fma_f32 v49, v4, v48, v16
	s_waitcnt vmcnt(24)
	v_fma_f32 v50, v4, v49, v17
	s_waitcnt vmcnt(23)
	v_fma_f32 v51, v4, v50, v18
	s_waitcnt vmcnt(22)
	v_fma_f32 v52, v4, v51, v19
	s_waitcnt vmcnt(21)
	v_fma_f32 v53, v4, v52, v20
	s_waitcnt vmcnt(20)
	v_fma_f32 v54, v4, v53, v21
	s_waitcnt vmcnt(19)
	v_fma_f32 v55, v4, v54, v22
	s_waitcnt vmcnt(18)
	v_fma_f32 v56, v4, v55, v23
	s_waitcnt vmcnt(17)
	v_fma_f32 v57, v4, v56, v24
	s_waitcnt vmcnt(16)
	v_fma_f32 v58, v4, v57, v25
	s_waitcnt vmcnt(15)
	v_fma_f32 v59, v4, v58, v26
	s_waitcnt vmcnt(14)
	v_fma_f32 v60, v4, v59, v27
	s_waitcnt vmcnt(13)
	v_fma_f32 v61, v4, v60, v28
	s_waitcnt vmcnt(12)
	v_fma_f32 v62, v4, v61, v29
	s_waitcnt vmcnt(11)
	v_fma_f32 v63, v4, v62, v30
	s_waitcnt vmcnt(10)
	v_fma_f32 v64, v4, v63, v31
	s_waitcnt vmcnt(9)
	v_fma_f32 v65, v4, v64, v32
	s_waitcnt vmcnt(8)
	v_fma_f32 v66, v4, v65, v33
	s_waitcnt vmcnt(7)
	v_fma_f32 v67, v4, v66, v34
	s_waitcnt vmcnt(6)
	v_fma_f32 v68, v4, v67, v35
	s_waitcnt vmcnt(5)
	v_fma_f32 v69, v4, v68, v36
	s_waitcnt vmcnt(4)
	v_fma_f32 v70, v4, v69, v37
	s_waitcnt vmcnt(3)
	v_fma_f32 v71, v4, v70, v38
	s_waitcnt vmcnt(2)
	v_fma_f32 v72, v4, v71, v39
	s_waitcnt vmcnt(1)
	v_fma_f32 v73, v4, v72, v40
	s_waitcnt vmcnt(0)
	v_fma_f32 v74, v4, v73, v41
	ds_write_b32 v7, v74
	s_waitcnt lgkmcnt(0)
	s_barrier
; __device__ __forceinline__ unsigned cvt_pk_bf16(float lo, float hi) { unsigned r; asm volatile("v_cvt_pk_bf16_f32 %0, %1, %2" : "=v"(r) : "v"(lo), "v"(hi)); return r; }
; #define GAS __attribute__((address_space(1)))
; __device__ __forceinline__ float lg2_gamma(int h) { return log2f(1.0f - __builtin_amdgcn_exp2f(-5.0f - (float)h)); }
; __device__ __forceinline__ void scan_phase(const GAS float* kvT, GAS bf16_t* st, int tid, int G, int bid) {
;     for (int idx = bid * 512 + tid; idx < 24576; idx += G * 512) {
;         const int h = idx >> 12; const float dec = __builtin_amdgcn_exp2f(lg2_gamma(h) * 128.0f);
;         float S = 0.f;
;         for (int n0 = 0; n0 < 128; n0 += 64) {
;             float kv[64];
; #pragma unroll
;             for (int i = 0; i < 64; ++i) kv[i] = kvT[(size_t)(n0 + i) * 24576 + idx];
; #pragma unroll
;             for (int i = 0; i < 64; ++i) { st[(size_t)(n0 + i) * 24576 + idx] = (bf16_t)(cvt_pk_bf16(S, 0.f) & 0xffffu); S = S * dec + kv[i]; }
;         }
	ds_read_b32 v10, v8
	ds_read_b32 v11, v8 offset:512
	ds_read_b32 v12, v8 offset:1024
	v_mul_u32_u24_e32 v6, 0x180000, v1
	v_mov_b32_e32 v9, 0
	v_cmp_eq_u32_e32 vcc, 1, v1
	v_lshl_add_u32 v6, v3, 1, v6
	s_waitcnt lgkmcnt(0)
	v_cndmask_b32_e32 v9, v9, v10, vcc
	v_fma_f32 v11, v5, v10, v11
	v_cmp_eq_u32_e32 vcc, 2, v1
	v_fma_f32 v12, v5, v11, v12
	s_nop 0
	v_cndmask_b32_e32 v9, v9, v11, vcc
	v_cmp_eq_u32_e32 vcc, 3, v1
	s_nop 1
	v_cndmask_b32_e32 v9, v9, v12, vcc
	v_add_f32_e32 v13, v9, v42
	v_mul_f32_e32 v9, v9, v4
	v_cvt_pk_bf16_f32 v13, v13, v179
	global_store_short v6, v13, s[16:17]
	v_add_u32_e32 v6, 0xc000, v6
	v_add_f32_e32 v14, v9, v43
	v_mul_f32_e32 v9, v9, v4
	v_cvt_pk_bf16_f32 v14, v14, v179
	global_store_short v6, v14, s[16:17]
	v_add_u32_e32 v6, 0xc000, v6
	v_add_f32_e32 v15, v9, v44
	v_mul_f32_e32 v9, v9, v4
	v_cvt_pk_bf16_f32 v15, v15, v179
	global_store_short v6, v15, s[16:17]
	v_add_u32_e32 v6, 0xc000, v6
	v_add_f32_e32 v16, v9, v45
	v_mul_f32_e32 v9, v9, v4
	v_cvt_pk_bf16_f32 v16, v16, v179
	global_store_short v6, v16, s[16:17]
	v_add_u32_e32 v6, 0xc000, v6
	v_add_f32_e32 v17, v9, v46
	v_mul_f32_e32 v9, v9, v4
	v_cvt_pk_bf16_f32 v17, v17, v179
	global_store_short v6, v17, s[16:17]
	v_add_u32_e32 v6, 0xc000, v6
	v_add_f32_e32 v18, v9, v47
	v_mul_f32_e32 v9, v9, v4
	v_cvt_pk_bf16_f32 v18, v18, v179
	global_store_short v6, v18, s[16:17]
	v_add_u32_e32 v6, 0xc000, v6
	v_add_f32_e32 v19, v9, v48
	v_mul_f32_e32 v9, v9, v4
	v_cvt_pk_bf16_f32 v19, v19, v179
	global_store_short v6, v19, s[16:17]
	v_add_u32_e32 v6, 0xc000, v6
	v_add_f32_e32 v20, v9, v49
	v_mul_f32_e32 v9, v9, v4
	v_cvt_pk_bf16_f32 v20, v20, v179
	global_store_short v6, v20, s[16:17]
	v_add_u32_e32 v6, 0xc000, v6
	v_add_f32_e32 v13, v9, v50
	v_mul_f32_e32 v9, v9, v4
	v_cvt_pk_bf16_f32 v13, v13, v179
	global_store_short v6, v13, s[16:17]
	v_add_u32_e32 v6, 0xc000, v6
	v_add_f32_e32 v14, v9, v51
	v_mul_f32_e32 v9, v9, v4
	v_cvt_pk_bf16_f32 v14, v14, v179
	global_store_short v6, v14, s[16:17]
	v_add_u32_e32 v6, 0xc000, v6
	v_add_f32_e32 v15, v9, v52
	v_mul_f32_e32 v9, v9, v4
	v_cvt_pk_bf16_f32 v15, v15, v179
	global_store_short v6, v15, s[16:17]
	v_add_u32_e32 v6, 0xc000, v6
	v_add_f32_e32 v16, v9, v53
	v_mul_f32_e32 v9, v9, v4
	v_cvt_pk_bf16_f32 v16, v16, v179
	global_store_short v6, v16, s[16:17]
	v_add_u32_e32 v6, 0xc000, v6
	v_add_f32_e32 v17, v9, v54
	v_mul_f32_e32 v9, v9, v4
	v_cvt_pk_bf16_f32 v17, v17, v179
	global_store_short v6, v17, s[16:17]
	v_add_u32_e32 v6, 0xc000, v6
	v_add_f32_e32 v18, v9, v55
	v_mul_f32_e32 v9, v9, v4
	v_cvt_pk_bf16_f32 v18, v18, v179
	global_store_short v6, v18, s[16:17]
	v_add_u32_e32 v6, 0xc000, v6
	v_add_f32_e32 v19, v9, v56
	v_mul_f32_e32 v9, v9, v4
	v_cvt_pk_bf16_f32 v19, v19, v179
	global_store_short v6, v19, s[16:17]
	v_add_u32_e32 v6, 0xc000, v6
	v_add_f32_e32 v20, v9, v57
	v_mul_f32_e32 v9, v9, v4
	v_cvt_pk_bf16_f32 v20, v20, v179
	global_store_short v6, v20, s[16:17]
	v_add_u32_e32 v6, 0xc000, v6
	v_add_f32_e32 v13, v9, v58
	v_mul_f32_e32 v9, v9, v4
	v_cvt_pk_bf16_f32 v13, v13, v179
	global_store_short v6, v13, s[16:17]
	v_add_u32_e32 v6, 0xc000, v6
	v_add_f32_e32 v14, v9, v59
	v_mul_f32_e32 v9, v9, v4
	v_cvt_pk_bf16_f32 v14, v14, v179
	global_store_short v6, v14, s[16:17]
	v_add_u32_e32 v6, 0xc000, v6
	v_add_f32_e32 v15, v9, v60
	v_mul_f32_e32 v9, v9, v4
	v_cvt_pk_bf16_f32 v15, v15, v179
	global_store_short v6, v15, s[16:17]
	v_add_u32_e32 v6, 0xc000, v6
	v_add_f32_e32 v16, v9, v61
	v_mul_f32_e32 v9, v9, v4
	v_cvt_pk_bf16_f32 v16, v16, v179
	global_store_short v6, v16, s[16:17]
	v_add_u32_e32 v6, 0xc000, v6
	v_add_f32_e32 v17, v9, v62
	v_mul_f32_e32 v9, v9, v4
	v_cvt_pk_bf16_f32 v17, v17, v179
	global_store_short v6, v17, s[16:17]
	v_add_u32_e32 v6, 0xc000, v6
	v_add_f32_e32 v18, v9, v63
	v_mul_f32_e32 v9, v9, v4
	v_cvt_pk_bf16_f32 v18, v18, v179
	global_store_short v6, v18, s[16:17]
	v_add_u32_e32 v6, 0xc000, v6
	v_add_f32_e32 v19, v9, v64
	v_mul_f32_e32 v9, v9, v4
	v_cvt_pk_bf16_f32 v19, v19, v179
	global_store_short v6, v19, s[16:17]
	v_add_u32_e32 v6, 0xc000, v6
	v_add_f32_e32 v20, v9, v65
	v_mul_f32_e32 v9, v9, v4
	v_cvt_pk_bf16_f32 v20, v20, v179
	global_store_short v6, v20, s[16:17]
	v_add_u32_e32 v6, 0xc000, v6
	v_add_f32_e32 v13, v9, v66
	v_mul_f32_e32 v9, v9, v4
	v_cvt_pk_bf16_f32 v13, v13, v179
	global_store_short v6, v13, s[16:17]
	v_add_u32_e32 v6, 0xc000, v6
	v_add_f32_e32 v14, v9, v67
	v_mul_f32_e32 v9, v9, v4
	v_cvt_pk_bf16_f32 v14, v14, v179
	global_store_short v6, v14, s[16:17]
	v_add_u32_e32 v6, 0xc000, v6
	v_add_f32_e32 v15, v9, v68
	v_mul_f32_e32 v9, v9, v4
	v_cvt_pk_bf16_f32 v15, v15, v179
	global_store_short v6, v15, s[16:17]
	v_add_u32_e32 v6, 0xc000, v6
	v_add_f32_e32 v16, v9, v69
	v_mul_f32_e32 v9, v9, v4
	v_cvt_pk_bf16_f32 v16, v16, v179
	global_store_short v6, v16, s[16:17]
	v_add_u32_e32 v6, 0xc000, v6
	v_add_f32_e32 v17, v9, v70
	v_mul_f32_e32 v9, v9, v4
	v_cvt_pk_bf16_f32 v17, v17, v179
	global_store_short v6, v17, s[16:17]
	v_add_u32_e32 v6, 0xc000, v6
	v_add_f32_e32 v18, v9, v71
	v_mul_f32_e32 v9, v9, v4
	v_cvt_pk_bf16_f32 v18, v18, v179
	global_store_short v6, v18, s[16:17]
	v_add_u32_e32 v6, 0xc000, v6
	v_add_f32_e32 v19, v9, v72
	v_mul_f32_e32 v9, v9, v4
	v_cvt_pk_bf16_f32 v19, v19, v179
	global_store_short v6, v19, s[16:17]
	v_add_u32_e32 v6, 0xc000, v6
	v_add_f32_e32 v20, v9, v73
	v_cvt_pk_bf16_f32 v20, v20, v179
	global_store_short v6, v20, s[16:17]
